# grid barrier: XCC leader releases its XCC's pollers (generation atomic) before its own L1 invalidate instead of after; on top of stage B
# speedup vs baseline: 1.0049x; 1.0049x over previous
; DI unsigned xb_ld(unsigned* p)              { return __hip_atomic_load(p, __ATOMIC_RELAXED, __HIP_MEMORY_SCOPE_AGENT); }
; DI unsigned xb_add(unsigned* p, unsigned v) { return __hip_atomic_fetch_add(p, v, __ATOMIC_RELAXED, __HIP_MEMORY_SCOPE_AGENT); }
; #define XB_SPIN(cond, bar) do { unsigned _sp = 0; while (cond) { __builtin_amdgcn_s_sleep(1); \
;     if ((++_sp & 255u) == 0u) { if (xb_ld(&(bar)[XB_TMO])) break; if (_sp > XB_SPIN_CAP) { atomicAdd(&(bar)[XB_TMO], 1u); break; } } } } while (0)
; template <class Hook = NoHook> DI void xcd_barrier(const XcdBarrier& b, const Hook& hook = Hook()) {
;     ...
;             const unsigned og = xb_add(&bar[XB_TOP], 1u);
;             const unsigned tg = og / nx;
;             if (og + 1u == (tg + 1u) * nx) xb_add(&bar[XB_TOPGEN], 1u);
;             else XB_SPIN(xb_ld(&bar[XB_TOPGEN]) == tg, bar);
;             __builtin_amdgcn_fence(__ATOMIC_ACQUIRE, "agent");
;             xb_add(&bar[XB_XGEN(b.x)], 1u);
;             asm volatile("s_waitcnt vmcnt(0)" ::: "memory");
.LBB0_119:
	s_or_b64 exec, exec, s[10:11]
	s_mov_b64 s[10:11], exec
	v_mbcnt_lo_u32_b32 v0, s10, 0
	v_mbcnt_hi_u32_b32 v0, s11, v0
	v_cmp_eq_u32_e32 vcc, 0, v0
	s_waitcnt vmcnt(0)
	s_and_saveexec_b64 s[12:13], vcc
	s_cbranch_execz .LBB0_121
	s_bcnt1_i32_b64 s10, s[10:11]
	v_mov_b32_e32 v0, 0x2000
	v_mov_b32_e32 v1, s10
	global_atomic_add v0, v1, s[4:5] offset:1024
.LBB0_121:
	s_or_b64 exec, exec, s[12:13]
	buffer_inv sc1
	s_waitcnt vmcnt(0)

; DI unsigned xb_ld(unsigned* p)              { return __hip_atomic_load(p, __ATOMIC_RELAXED, __HIP_MEMORY_SCOPE_AGENT); }
; DI unsigned xb_add(unsigned* p, unsigned v) { return __hip_atomic_fetch_add(p, v, __ATOMIC_RELAXED, __HIP_MEMORY_SCOPE_AGENT); }
; #define XB_SPIN(cond, bar) do { unsigned _sp = 0; while (cond) { __builtin_amdgcn_s_sleep(1); \
;     if ((++_sp & 255u) == 0u) { if (xb_ld(&(bar)[XB_TMO])) break; if (_sp > XB_SPIN_CAP) { atomicAdd(&(bar)[XB_TMO], 1u); break; } } } } while (0)
; template <class Hook = NoHook> DI void xcd_barrier(const XcdBarrier& b, const Hook& hook = Hook()) {
;     ...
;             const unsigned og = xb_add(&bar[XB_TOP], 1u);
;             const unsigned tg = og / nx;
;             if (og + 1u == (tg + 1u) * nx) xb_add(&bar[XB_TOPGEN], 1u);
;             else XB_SPIN(xb_ld(&bar[XB_TOPGEN]) == tg, bar);
;             __builtin_amdgcn_fence(__ATOMIC_ACQUIRE, "agent");
;             xb_add(&bar[XB_XGEN(b.x)], 1u);
;             asm volatile("s_waitcnt vmcnt(0)" ::: "memory");
.LBB0_390:
	s_or_b64 exec, exec, s[14:15]
	s_mov_b64 s[14:15], exec
	v_mbcnt_lo_u32_b32 v0, s14, 0
	v_mbcnt_hi_u32_b32 v0, s15, v0
	v_cmp_eq_u32_e32 vcc, 0, v0
	s_waitcnt vmcnt(0)
	s_and_saveexec_b64 s[16:17], vcc
	s_cbranch_execz .LBB0_392
	s_bcnt1_i32_b64 s14, s[14:15]
	v_mov_b32_e32 v0, 0x2000
	v_mov_b32_e32 v1, s14
	global_atomic_add v0, v1, s[0:1] offset:1024
.LBB0_392:
	s_or_b64 exec, exec, s[16:17]
	buffer_inv sc1
	s_waitcnt vmcnt(0)

; DI unsigned xb_ld(unsigned* p)              { return __hip_atomic_load(p, __ATOMIC_RELAXED, __HIP_MEMORY_SCOPE_AGENT); }
; DI unsigned xb_add(unsigned* p, unsigned v) { return __hip_atomic_fetch_add(p, v, __ATOMIC_RELAXED, __HIP_MEMORY_SCOPE_AGENT); }
; #define XB_SPIN(cond, bar) do { unsigned _sp = 0; while (cond) { __builtin_amdgcn_s_sleep(1); \
;     if ((++_sp & 255u) == 0u) { if (xb_ld(&(bar)[XB_TMO])) break; if (_sp > XB_SPIN_CAP) { atomicAdd(&(bar)[XB_TMO], 1u); break; } } } } while (0)
; template <class Hook = NoHook> DI void xcd_barrier(const XcdBarrier& b, const Hook& hook = Hook()) {
;     ...
;             const unsigned og = xb_add(&bar[XB_TOP], 1u);
;             const unsigned tg = og / nx;
;             if (og + 1u == (tg + 1u) * nx) xb_add(&bar[XB_TOPGEN], 1u);
;             else XB_SPIN(xb_ld(&bar[XB_TOPGEN]) == tg, bar);
;             __builtin_amdgcn_fence(__ATOMIC_ACQUIRE, "agent");
;             xb_add(&bar[XB_XGEN(b.x)], 1u);
;             asm volatile("s_waitcnt vmcnt(0)" ::: "memory");
.LBB0_528:
	s_or_b64 exec, exec, s[6:7]
	s_mov_b64 s[6:7], exec
	v_mbcnt_lo_u32_b32 v128, s6, 0
	v_mbcnt_hi_u32_b32 v128, s7, v128
	v_cmp_eq_u32_e32 vcc, 0, v128
	s_waitcnt vmcnt(0)
	s_and_saveexec_b64 s[10:11], vcc
	s_cbranch_execz .LBB0_530
	s_bcnt1_i32_b64 s3, s[6:7]
	v_mov_b32_e32 v128, 0x2000
	v_mov_b32_e32 v129, s3
	global_atomic_add v128, v129, s[0:1] offset:1024
.LBB0_530:
	s_or_b64 exec, exec, s[10:11]
	buffer_inv sc1
	s_waitcnt vmcnt(0)
